# SSD chunk loop: 14 copies of never-used intra-chunk G fragments (current -> next register set) removed
# baseline (speedup 1.0000x reference)
.LBB0_649:
	s_add_i32 s35, s23, 1
	s_cmp_lt_u32 s35, s34
	s_cselect_b32 s23, s35, s23
	v_readlane_b32 s0, v243, 41
	s_sub_i32 s24, s0, s23
	s_and_b64 s[0:1], s[8:9], exec
	s_cselect_b32 s0, s23, s24
	s_ashr_i32 s1, s0, 31
	s_lshl_b64 s[0:1], s[0:1], 7
	s_add_u32 s0, s0, s4
	v_readlane_b32 s24, v245, 25
	s_addc_u32 s1, s1, s5
	v_readlane_b32 s25, v245, 26
	s_nop 1
	s_mul_hi_u32 s99, s0, 0x3000
	s_mul_i32 s98, s0, 0x3000
	s_add_u32 s98, s98, s24
	s_addc_u32 s99, s99, s25
	global_load_dwordx4 v[44:47], v253, s[98:99] offset:64
	global_load_dwordx4 v[48:51], v253, s[98:99] offset:128
	global_load_dwordx4 v[60:63], v253, s[98:99]
	global_load_dwordx4 v[52:55], v253, s[98:99] offset:192
	s_and_b64 vcc, exec, s[10:11]
	s_cbranch_vccnz .LBB0_653
	s_lshr_b64 s[24:25], s[0:1], 4
	s_add_u32 s24, s24, s84
	s_addc_u32 s25, s25, s85
	s_lshl_b64 s[24:25], s[24:25], 15
	s_add_u32 s24, s24, s100
	s_addc_u32 s25, s25, s101
	global_load_dwordx4 v[56:59], v254, s[24:25]
	s_and_b64 vcc, exec, s[12:13]
	s_cbranch_vccz .LBB0_654
.LBB0_651:
	s_and_b64 vcc, exec, s[14:15]
	s_cbranch_vccnz .LBB0_655
.LBB0_652:
	s_lshr_b64 s[24:25], s[0:1], 4
	s_add_u32 s24, s24, s84
	s_addc_u32 s25, s25, s85
	s_lshl_b64 s[24:25], s[24:25], 15
	s_add_u32 s24, s24, s100
	s_addc_u32 s25, s25, s101
	global_load_dwordx4 v[68:71], v254, s[24:25] offset:128
	s_andn2_b64 vcc, exec, s[90:91]
	s_cbranch_vccz .LBB0_656
	s_branch .LBB0_657
.LBB0_653:
	s_and_b64 vcc, exec, s[12:13]
	s_cbranch_vccnz .LBB0_651
.LBB0_654:
	s_lshr_b64 s[24:25], s[0:1], 4
	s_add_u32 s24, s24, s84
	s_addc_u32 s25, s25, s85
	s_lshl_b64 s[24:25], s[24:25], 15
	s_add_u32 s24, s24, s100
	s_addc_u32 s25, s25, s101
	global_load_dwordx4 v[64:67], v254, s[24:25] offset:64
	s_and_b64 vcc, exec, s[14:15]
	s_cbranch_vccz .LBB0_652
.LBB0_655:
	s_andn2_b64 vcc, exec, s[90:91]
	s_cbranch_vccnz .LBB0_657
